# prompt attention: in the even half-step the next tile's K/V/bias staging loads are issued right after the barrier (before QK^T) instead of after QK^T+softmax finish; v[200:201] borrowed as address tem
# speedup vs baseline: 1.0036x; 1.0036x over previous
; #define SBAR() __builtin_amdgcn_sched_barrier(0)
; #define VMW() asm volatile("s_waitcnt vmcnt(0)" ::: "memory")
; #define SLOAD_H(Kp, Vp, Cp, k0) do { S.st_b0 = (Cp)[(unsigned)((k0) + sr + 32 * (tid & 1))]; S.st_v0 = load8<TIn>(ROW(Vp, k0, sr)); S.st_v1 = load8<TIn>(ROW(Vp, k0, 32 + sr));              \
;                          S.st_k0 = load8<TIn>(ROW(Kp, k0, sr)); S.st_k1 = load8<TIn>(ROW(Kp, k0, 32 + sr)); } while (0)
; #define SWRITE_HK(bf) do { B_lds[(bf) * 64 + sr + 32 * (tid & 1)] = S.st_b0; *(bf16x8*)(K_lds + (bf) * SHM_K + kws) = S.st_k0; *(bf16x8*)(K_lds + (bf) * SHM_K + kws + 32 * 256) = S.st_k1; } while (0)
; template <class TIn, class TOut>
; __device__ __forceinline__ void causal_swa_prime(const BlockRef<TIn, TOut>& cur, int W, char* lds, Seam<TIn>& S) {
;     constexpr bool F32 = same_t<TIn, float>::v;
;     const int tid = otid(), wid = __builtin_amdgcn_readfirstlane(tid >> 6), lane = tid & 63, r32 = lane & 31, hi = lane >> 5;
;     const int sr = tid >> 4, sc = (tid & 15) * 8, kws = KSWZ(sr, sc * 2); char* K_lds = lds + 2 * SHM_V; float* B_lds = (float*)(lds + 2 * SHM_V + 2 * SHM_K + NW * 64 * 4);
;     const int kb0 = swa_jlo(cur.P0, W) * KVBLK;
;     for (int d0 = 0; d0 < 8; ++d0) S.qr[d0] = load8<TIn>(cur.Q + (unsigned)((wid * QBLK + r32) * PITCH + d0 * 16 + hi * 8));
;     if constexpr (F32) { SLOAD_F((const float*)cur.K, kb0); VMW(); SWRITE_KF(0); SBAR(); SLOAD_F((const float*)cur.V, kb0); }
;     else { SLOAD_H(cur.K, cur.V, cur.CB, kb0); VMW(); SWRITE_HK(0); }
;     __syncthreads();
; }
;     ...
;     const T* Q = (const T*)(a.p->ws + WS_R0); const T* K = (const T*)(a.p->ws + WS_R0 + RSZ); const T* V = (const T*)(a.p->ws + WS_R0 + 2 * RSZ); const T* Z = (const T*)(a.p->ws + WS_R0 + 3 * RSZ); T* O = (T*)(a.p->ws + (mode == 1 ? WS_DUMMY : WS_R0));
;     const float* CB = (const float*)(a.p->ws + WS_CBP);
;     char* lds = (char*)ldsb;
;     constexpr int nqb = SEQ / QB, nx = nqb / 2, total = nx * NBH;
;     const int stride = gridDim.x;
;     int L = (gridDim.x == 256) ? (int)((blockIdx.x & 7) * 32 + (blockIdx.x >> 3)) : (int)blockIdx.x;
;     if (mode == 2) L = total;
;     if (L < total) {
;     ...
;         BlockRef<T, T> cur, nxt; int pass = 0;
;         MKREF(cur, L, 0);
;         Seam<T> S;
;         causal_swa_prime<T, T>(cur, SEQ, lds, S);
.LBB0_1232:
	s_or_b64 exec, exec, s[2:3]
	s_mov_b64 s[8:9], s[50:51]
	s_waitcnt lgkmcnt(0)
	s_barrier
	s_load_dwordx2 s[6:7], s[8:9], 0xa8
	v_readlane_b32 s2, v254, 12
	v_readlane_b32 s3, v254, 13
	s_waitcnt lgkmcnt(0)
	s_add_u32 s10, s6, 0xf000000
	s_addc_u32 s11, s7, 0
	s_add_u32 s12, s6, 0x27300000
	s_addc_u32 s13, s7, 0
	s_andn2_b64 vcc, exec, s[2:3]
	s_cbranch_vccnz .LBB0_1413
	v_mov_b32_e32 v201, 0
	s_add_u32 s0, s6, 0x17100000
	s_addc_u32 s46, s7, 0
	s_add_u32 s47, s6, 0x1f200000
	s_addc_u32 s48, s7, 0
	s_add_u32 s49, s6, 0xec00000
	s_addc_u32 s50, s7, 0
	v_readlane_b32 s2, v254, 60
	v_readlane_b32 s3, v254, 61
	s_add_u32 s36, s10, s2
	s_addc_u32 s37, s11, s3
	s_add_u32 s54, s12, s2
	s_addc_u32 s55, s13, s3
	v_readlane_b32 s2, v254, 62
	s_mov_b32 s40, s62
	v_readlane_b32 s3, v254, 63
	s_add_u32 s62, s0, s2
	s_addc_u32 s63, s46, s3
	s_add_u32 s64, s47, s2
	s_addc_u32 s65, s48, s3
	v_readlane_b32 s2, v254, 15
	v_readlane_b32 s3, v254, 16
	s_add_u32 s66, s49, s2
	s_getreg_b32 s2, hwreg(HW_REG_HW_ID, 0, 6)
	s_addc_u32 s67, s50, s3
	s_and_b32 s2, s2, 63
	s_lshl_b32 s2, s2, 2
	s_add_i32 s2, s2, 0
	s_add_i32 s2, s2, 0x23e00
	v_mov_b32_e32 v0, s2
	ds_read_b32 v0, v0
	v_mbcnt_lo_u32_b32 v4, -1, 0
	v_readlane_b32 s57, v254, 17
	v_mbcnt_hi_u32_b32 v4, -1, v4
	s_mov_b32 s51, 0
	s_waitcnt lgkmcnt(0)
	v_readfirstlane_b32 s2, v0
	v_lshrrev_b32_e32 v2, 2, v4
	v_and_b32_e32 v2, 8, v2
	v_lshl_add_u32 v12, s2, 6, v4
	v_ashrrev_i32_e32 v13, 4, v12
	v_readfirstlane_b32 s2, v12
	s_lshr_b32 s2, s2, 1
	s_and_b32 s2, s2, 0x1fffe0
	v_and_or_b32 v0, v4, 31, s2
	v_lshl_or_b32 v0, v0, 11, v2
	v_lshl_add_u64 v[2:3], v[0:1], 1, s[36:37]
	v_lshlrev_b32_e32 v0, 3, v4
	v_and_b32_e32 v14, 0x78, v0
	v_readlane_b32 s2, v254, 18
	v_lshlrev_b32_e32 v0, 5, v4
	v_and_b32_e32 v15, 32, v0
	v_add_u32_e32 v6, s2, v13
	v_add_u32_e32 v0, v6, v15
	v_lshl_add_u64 v[4:5], v[0:1], 2, s[66:67]
	v_lshl_or_b32 v0, v6, 11, v14
	global_load_dwordx4 v[172:175], v[2:3], off
	global_load_dwordx4 v[168:171], v[2:3], off offset:32
	global_load_dwordx4 v[164:167], v[2:3], off offset:64
	global_load_dwordx4 v[160:163], v[2:3], off offset:96
	global_load_dword v176, v[4:5], off
	v_lshlrev_b64 v[4:5], 1, v[0:1]
	v_add_u32_e32 v0, 0x10000, v0
	v_lshlrev_b64 v[6:7], 1, v[0:1]
	v_lshl_add_u64 v[8:9], s[64:65], 0, v[6:7]
	v_lshl_add_u64 v[6:7], s[62:63], 0, v[6:7]
	v_lshl_add_u64 v[10:11], s[62:63], 0, v[4:5]
	global_load_dwordx4 v[112:115], v[8:9], off
	global_load_dwordx4 v[116:119], v[10:11], off
	global_load_dwordx4 v[120:123], v[6:7], off
	global_load_dwordx4 v[156:159], v[2:3], off offset:128
	global_load_dwordx4 v[152:155], v[2:3], off offset:160
	global_load_dwordx4 v[148:151], v[2:3], off offset:192
	global_load_dwordx4 v[144:147], v[2:3], off offset:224
	v_lshl_add_u64 v[2:3], s[64:65], 0, v[4:5]
	global_load_dwordx4 v[124:127], v[2:3], off
	v_lshlrev_b32_e32 v0, 1, v14
	s_movk_i32 s2, 0x70
	s_waitcnt vmcnt(0)
	v_lshlrev_b32_e32 v2, 2, v15
	v_bitop3_b32 v0, v0, v12, s2 bitop3:0x78
	v_lshlrev_b32_e32 v4, 2, v13
	v_readlane_b32 s2, v255, 3
	v_readlane_b32 s52, v254, 14
	s_mov_b32 s53, s57
	s_mov_b64 s[14:15], s[36:37]
	s_mov_b64 s[16:17], s[54:55]
	s_mov_b64 s[18:19], s[64:65]
	s_mov_b64 s[24:25], s[66:67]
	v_lshlrev_b32_e32 v3, 8, v13
	v_add3_u32 v2, s2, v4, v2
	s_mov_b64 s[26:27], s[62:63]
	v_add3_u32 v0, 0, v3, v0
	s_waitcnt vmcnt(8)
	ds_write_b32 v2, v176
	s_waitcnt vmcnt(6)
	ds_write_b128 v0, v[116:119] offset:32768
	s_waitcnt vmcnt(5)
	ds_write_b128 v0, v[120:123] offset:40960
	s_waitcnt lgkmcnt(0)
	s_barrier
	s_branch .LBB0_1235

; __device__ __forceinline__ void partialSM(f32x16& p0, f32x16& p1, float& m_reg, float& mn, float& alpha) {
;     ...
;     for (int r = 0; r < 16; ++r) p0[r] = fmaf(p0[r], C2, mnL); for (int r = 0; r < 16; ++r) p1[r] = fmaf(p1[r], C2, mnL);
;     for (int r = 0; r < 16; ++r) p0[r] = __builtin_amdgcn_exp2f(p0[r]);
.LBB0_1253:
	v_cndmask_b32_e64 v247, v0, v180, s[4:5]
	v_mul_f32_e32 v0, 0xbe0293ee, v247
	v_fmamk_f32 v80, v100, 0x3e0293ee, v0
	v_fmamk_f32 v81, v101, 0x3e0293ee, v0
	v_fmamk_f32 v82, v102, 0x3e0293ee, v0
	v_fmamk_f32 v83, v103, 0x3e0293ee, v0
	v_fmamk_f32 v116, v104, 0x3e0293ee, v0
	v_fmamk_f32 v117, v105, 0x3e0293ee, v0
	v_fmamk_f32 v118, v106, 0x3e0293ee, v0
	v_fmamk_f32 v119, v107, 0x3e0293ee, v0
	v_fmamk_f32 v120, v108, 0x3e0293ee, v0
	v_fmamk_f32 v121, v109, 0x3e0293ee, v0
	v_fmamk_f32 v122, v110, 0x3e0293ee, v0
	v_fmamk_f32 v123, v111, 0x3e0293ee, v0
	v_fmamk_f32 v112, v112, 0x3e0293ee, v0
	v_fmamk_f32 v113, v113, 0x3e0293ee, v0
	v_fmamk_f32 v114, v114, 0x3e0293ee, v0
	v_fmamk_f32 v115, v115, 0x3e0293ee, v0
	v_fmamk_f32 v100, v84, 0x3e0293ee, v0
	v_fmamk_f32 v109, v85, 0x3e0293ee, v0
	v_fmamk_f32 v110, v86, 0x3e0293ee, v0
	v_fmamk_f32 v111, v87, 0x3e0293ee, v0
	v_fmamk_f32 v180, v88, 0x3e0293ee, v0
	v_fmamk_f32 v101, v89, 0x3e0293ee, v0
	v_fmamk_f32 v102, v90, 0x3e0293ee, v0
	v_fmamk_f32 v103, v91, 0x3e0293ee, v0
	v_fmamk_f32 v104, v92, 0x3e0293ee, v0
	v_fmamk_f32 v105, v93, 0x3e0293ee, v0
	v_fmamk_f32 v106, v94, 0x3e0293ee, v0
	v_fmamk_f32 v107, v95, 0x3e0293ee, v0
	v_exp_f32_e32 v80, v80
	v_exp_f32_e32 v81, v81
	v_exp_f32_e32 v82, v82
	v_exp_f32_e32 v83, v83
	v_exp_f32_e32 v84, v116
	v_exp_f32_e32 v85, v117
	v_exp_f32_e32 v86, v118
	v_exp_f32_e32 v87, v119
	v_exp_f32_e32 v88, v120
	v_exp_f32_e32 v89, v121
	v_exp_f32_e32 v90, v122
	v_exp_f32_e32 v91, v123
	v_exp_f32_e32 v92, v112
	v_exp_f32_e32 v93, v113
	v_exp_f32_e32 v94, v114
	v_exp_f32_e32 v95, v115
	v_fmamk_f32 v108, v96, 0x3e0293ee, v0
	v_fmamk_f32 v181, v97, 0x3e0293ee, v0
	v_fmamk_f32 v182, v98, 0x3e0293ee, v0
	v_fmac_f32_e32 v0, 0x3e0293ee, v99
	s_waitcnt lgkmcnt(0)
	s_barrier
	s_add_i32 s4, s61, 1
	s_cmp_lt_i32 s4, s59
	s_cselect_b64 s[28:29], -1, 0
	s_cmp_ge_i32 s4, s59
	s_cbranch_scc1 .Lattn_h2_noload
	v_add_u32_e32 v200, 0x41, v248
	v_lshl_add_u64 v[2:3], v[200:201], 2, s[66:67]
	v_add_u32_e32 v200, 0x20000, v14
	v_lshlrev_b64 v[10:11], 1, v[200:201]
	v_add_u32_e32 v200, 0x30000, v14
	v_lshlrev_b64 v[12:13], 1, v[200:201]
	global_load_dword v246, v[2:3], off
	v_lshl_add_u64 v[2:3], s[64:65], 0, v[10:11]
	v_lshl_add_u64 v[6:7], s[64:65], 0, v[12:13]
	v_lshl_add_u64 v[10:11], s[62:63], 0, v[10:11]
	v_lshl_add_u64 v[176:177], s[62:63], 0, v[12:13]
	global_load_dwordx4 v[2:5], v[2:3], off
	s_nop 0
	global_load_dwordx4 v[6:9], v[6:7], off
	s_nop 0
	global_load_dwordx4 v[10:13], v[10:11], off
	s_nop 0
	global_load_dwordx4 v[176:179], v[176:177], off
; __device__ __forceinline__ void finishSM(f32x16& p0, f32x16& p1, float alpha, float& l_reg, bf16x8& pa0, bf16x8& pa1, bf16x8& pa2, bf16x8& pa3) {
;     for (int r = 0; r < 16; ++r) p1[r] = __builtin_amdgcn_exp2f(p1[r]);
;     float ps = 0; for (int r = 0; r < 16; ++r) ps += p0[r]; for (int r = 0; r < 16; ++r) ps += p1[r];
;     { auto rr = __builtin_amdgcn_permlane32_swap(__float_as_uint(ps), __float_as_uint(ps), false, false);
;       ps = __uint_as_float(rr[0]) + __uint_as_float(rr[1]); }
;     l_reg = l_reg * alpha + ps;
;     ...
;     PK4(p0, 0, pa0); PK4(p0, 8, pa1); PK4(p1, 0, pa2); PK4(p1, 8, pa3);
;     ...
; }
; template <int KB, bool SK>
; __device__ __forceinline__ void qkt(f32x16& p0, f32x16& p1, const char* K_lds, const float* B_lds, int r32, int hi, const bf16x8* qr, bool act) {
;     if (SK && !act) { const float NEG = -__builtin_inff();
; #pragma unroll
;         for (int r = 0; r < 16; ++r) { p0[r] = NEG; p1[r] = NEG; } return; }
;     ...
;     p0 = f32x16{}; p1 = f32x16{};
;     ...
;     p0 = *(const f32x16*)(B_lds + KB * 64 + hi * 32); p1 = *(const f32x16*)(B_lds + KB * 64 + hi * 32 + 16);
;     ...
;     const char* kb[4];
; #pragma unroll
;     for (int dd = 0; dd < 4; ++dd) kb[dd] = K_lds + KB * SHM_K + KSWZ(r32, (dd * 16 + hi * 8) * 2);
; #pragma unroll
;     for (int d0 = 0; d0 < 8; ++d0) { const char* a = kb[d0 & 3] + (d0 >> 2) * 128;
;         bf16x8 b0 = *reinterpret_cast<const bf16x8*>(a);
;         bf16x8 b1 = *reinterpret_cast<const bf16x8*>(a + 32 * 256);
;         p0 = __builtin_amdgcn_mfma_f32_32x32x16_bf16(b0, qr[d0], p0, 0, 0, 0);
;         p1 = __builtin_amdgcn_mfma_f32_32x32x16_bf16(b1, qr[d0], p1, 0, 0, 0); }
; }
.Lattn_h2_noload:
	ds_read_b128 v[128:131], v239
	ds_read_b128 v[132:135], v239 offset:16
	ds_read_b128 v[136:139], v239 offset:32
	ds_read_b128 v[140:143], v239 offset:48
	ds_read_b128 v[124:127], v239 offset:112
	ds_read_b128 v[120:123], v239 offset:96
	ds_read_b128 v[116:119], v239 offset:80
	ds_read_b128 v[112:115], v239 offset:64
	ds_read_b128 v[96:99], v235 offset:32768
	ds_read_b128 v[184:187], v235 offset:40960
	v_exp_f32_e32 v101, v101
	v_exp_f32_e32 v102, v102
	v_exp_f32_e32 v103, v103
	s_waitcnt lgkmcnt(1)
	v_mfma_f32_32x32x16_bf16 v[128:143], v[96:99], v[172:175], v[128:143]
	v_exp_f32_e32 v104, v104
	v_exp_f32_e32 v105, v105
	v_exp_f32_e32 v106, v106
	v_exp_f32_e32 v107, v107
	v_exp_f32_e32 v108, v108
	s_waitcnt lgkmcnt(0)
	v_mfma_f32_32x32x16_bf16 v[112:127], v[184:187], v[172:175], v[112:127]
	ds_read_b128 v[96:99], v234 offset:32768
	ds_read_b128 v[184:187], v234 offset:40960
	s_waitcnt lgkmcnt(1)
	v_mfma_f32_32x32x16_bf16 v[128:143], v[96:99], v[168:171], v[128:143]
	s_waitcnt lgkmcnt(0)
	v_mfma_f32_32x32x16_bf16 v[112:127], v[184:187], v[168:171], v[112:127]
	ds_read_b128 v[96:99], v233 offset:32768
	ds_read_b128 v[184:187], v233 offset:40960
	s_waitcnt lgkmcnt(1)
	v_mfma_f32_32x32x16_bf16 v[128:143], v[96:99], v[164:167], v[128:143]
	s_waitcnt lgkmcnt(0)
	v_mfma_f32_32x32x16_bf16 v[112:127], v[184:187], v[164:167], v[112:127]
	ds_read_b128 v[96:99], v232 offset:32768
	ds_read_b128 v[184:187], v232 offset:40960
	s_waitcnt lgkmcnt(1)
	v_mfma_f32_32x32x16_bf16 v[128:143], v[96:99], v[160:163], v[128:143]
	s_waitcnt lgkmcnt(0)
	v_mfma_f32_32x32x16_bf16 v[112:127], v[184:187], v[160:163], v[112:127]
	ds_read_b128 v[96:99], v235 offset:32896
	ds_read_b128 v[184:187], v235 offset:41088
	s_waitcnt lgkmcnt(1)
	v_mfma_f32_32x32x16_bf16 v[128:143], v[96:99], v[156:159], v[128:143]
	s_waitcnt lgkmcnt(0)
	v_mfma_f32_32x32x16_bf16 v[112:127], v[184:187], v[156:159], v[112:127]
	ds_read_b128 v[96:99], v234 offset:32896
	ds_read_b128 v[184:187], v234 offset:41088
	s_waitcnt lgkmcnt(1)
	v_mfma_f32_32x32x16_bf16 v[128:143], v[96:99], v[152:155], v[128:143]
	s_waitcnt lgkmcnt(0)
	v_mfma_f32_32x32x16_bf16 v[112:127], v[184:187], v[152:155], v[112:127]
	ds_read_b128 v[96:99], v233 offset:32896
	ds_read_b128 v[184:187], v233 offset:41088
	s_waitcnt lgkmcnt(1)
	v_mfma_f32_32x32x16_bf16 v[128:143], v[96:99], v[148:151], v[128:143]
	s_waitcnt lgkmcnt(0)
	v_mfma_f32_32x32x16_bf16 v[112:127], v[184:187], v[148:151], v[112:127]
	ds_read_b128 v[96:99], v232 offset:32896
	ds_read_b128 v[184:187], v232 offset:41088
	s_waitcnt lgkmcnt(1)
	v_mfma_f32_32x32x16_bf16 v[128:143], v[96:99], v[144:147], v[128:143]
	v_exp_f32_e32 v99, v111
	v_exp_f32_e32 v111, v0
	v_add_f32_e32 v0, 0, v80
	v_add_f32_e32 v0, v81, v0
	v_add_f32_e32 v0, v82, v0
	v_add_f32_e32 v0, v83, v0
	v_add_f32_e32 v0, v84, v0
	v_add_f32_e32 v0, v85, v0
	v_add_f32_e32 v0, v86, v0
	v_add_f32_e32 v0, v87, v0
	v_add_f32_e32 v0, v88, v0
	v_add_f32_e32 v0, v89, v0
	v_add_f32_e32 v0, v90, v0
	v_add_f32_e32 v0, v91, v0
	v_exp_f32_e32 v96, v100
	v_add_f32_e32 v0, v92, v0
	v_exp_f32_e32 v97, v109
	v_add_f32_e32 v0, v93, v0
	v_exp_f32_e32 v98, v110
	v_add_f32_e32 v0, v94, v0
	v_add_f32_e32 v0, v95, v0
	v_exp_f32_e32 v100, v180
	v_add_f32_e32 v0, v96, v0
	v_add_f32_e32 v0, v97, v0
	v_add_f32_e32 v0, v98, v0
	v_add_f32_e32 v0, v99, v0
	v_add_f32_e32 v0, v100, v0
	v_add_f32_e32 v0, v101, v0
	v_add_f32_e32 v0, v102, v0
	v_add_f32_e32 v0, v103, v0
	v_add_f32_e32 v0, v104, v0
	v_exp_f32_e32 v109, v181
	v_add_f32_e32 v0, v105, v0
	s_waitcnt lgkmcnt(0)
	v_mfma_f32_32x32x16_bf16 v[112:127], v[184:187], v[144:147], v[112:127]
	v_exp_f32_e32 v110, v182
	v_add_f32_e32 v0, v106, v0
	v_add_f32_e32 v0, v107, v0
	v_add_f32_e32 v0, v108, v0
	v_add_f32_e32 v0, v109, v0
	v_add_f32_e32 v0, v110, v0
	v_add_f32_e32 v249, v111, v0
	v_mov_b32_e32 v250, v249
	v_cvt_pk_bf16_f32 v180, v80, v81
	v_cvt_pk_bf16_f32 v181, v82, v83
	v_cvt_pk_bf16_f32 v182, v84, v85
	v_cvt_pk_bf16_f32 v183, v86, v87
	v_cvt_pk_bf16_f32 v184, v88, v89
	v_cvt_pk_bf16_f32 v185, v90, v91
	v_cvt_pk_bf16_f32 v186, v92, v93
	v_cvt_pk_bf16_f32 v187, v94, v95
	v_cvt_pk_bf16_f32 v188, v96, v97
	v_cvt_pk_bf16_f32 v189, v98, v99
	v_cvt_pk_bf16_f32 v190, v100, v101
	v_cvt_pk_bf16_f32 v191, v102, v103
	v_cvt_pk_bf16_f32 v192, v104, v105
	v_cvt_pk_bf16_f32 v193, v106, v107
	v_cvt_pk_bf16_f32 v194, v108, v109
	v_cvt_pk_bf16_f32 v195, v110, v111
	s_nop 1
	v_permlane32_swap_b32_e32 v249, v250
	v_permlane32_swap_b32_e32 v180, v182
	v_permlane32_swap_b32_e32 v181, v183
	v_permlane32_swap_b32_e32 v184, v186
	v_permlane32_swap_b32_e32 v185, v187
	v_permlane32_swap_b32_e32 v188, v190
	v_permlane32_swap_b32_e32 v189, v191
	v_permlane32_swap_b32_e32 v192, v194
	v_permlane32_swap_b32_e32 v193, v195

; __device__ __forceinline__ void sample_attn(const Args& a, int j, int bh, unsigned char* ldsb, bool dummy = false) {
;     constexpr int PP = 136;
;     float* wmx = (float*)ldsb;
;     bf16_t* Pb = (bf16_t*)(ldsb + 1024);
;     float* lfin = (float*)(ldsb + 1024 + 2 * 16 * PP * 2);
;     const int tid = otid(), lane = tid & 63, wid = __builtin_amdgcn_readfirstlane(tid >> 6), fr = lane & 15, fq = lane >> 4, b = bh >> 4, h = bh & 15;
;     const bf16_t* Qb = (const bf16_t*)(a.p->ws + WS_R0); const bf16_t* ZS = (const bf16_t*)(a.p->ws + WS_R0 + 3 * RSZ); bf16_t* O = (bf16_t*)(a.p->ws + (dummy ? WS_DUMMY : WS_R0));
;     const float* ck = a.p->in[2] + (size_t)(j * 8 + b) * PAST * EB + h * 128; const float* cv = a.p->in[3] + (size_t)(j * 8 + b) * PAST * EB + h * 128;
;     const float* nk = a.p->out + O_FKS + ((size_t)j * MS + b * TS) * EB + h * 128; const float* nv = a.p->out + O_FVS + ((size_t)j * MS + b * TS) * EB + h * 128;
;     const float* cb = (const float*)(a.p->ws + WS_CBS) + (size_t)bh * SKS;
;     ...
;     __syncthreads();
;     if (mode != 1) for (int bh = (int)gridDim.x - 1 - (int)blockIdx.x; bh < NBH; bh += gridDim.x) sample_attn(a, j, bh, ldsb, mode == 2);
.LBB0_1413:
	v_mov_b32_e32 v200, 64
	v_xor_b32_e32 v201, 8, v253
	v_readlane_b32 s2, v254, 19
	v_readlane_b32 s3, v254, 20
	s_andn2_b64 vcc, exec, s[2:3]
	s_barrier
	s_cbranch_vccnz .LBB0_1463
	s_lshl_b32 s0, s62, 18
	s_add_u32 s34, s6, 0xee80000
	s_addc_u32 s35, s7, 0
	v_readlane_b32 s36, v254, 56
	v_readlane_b32 s37, v254, 55
	s_branch .LBB0_1416
